# GEMM main loop: vmcnt wait for the late A-half stage moved one phase later (vmcnt 6->8 at phase 4, vmcnt(10) at phase 2): longer global->LDS prefetch distance
# speedup vs baseline: 1.0940x; 1.0030x over previous
.LBB0_894:
	s_add_i32 s6, s2, 2
	s_add_u32 s7, s64, s0
	s_addc_u32 s3, s65, s1
	s_add_u32 s8, s66, s0
	s_addc_u32 s9, s67, s1
	s_add_i32 s33, 0, 0x10000
	v_add_u32_e32 v160, s33, v165
	ds_read_b128 v[148:151], v160
	ds_read_b128 v[152:155], v160 offset:1024
	ds_read_b128 v[156:159], v160 offset:2048
	ds_read_b128 v[160:163], v160 offset:3072
	s_cmp_eq_u32 s92, s2
	s_cselect_b32 s2, s72, s7
	s_cselect_b32 s3, s73, s3
	s_cselect_b32 s9, s75, s9
	s_cselect_b32 s8, s74, s8
	v_lshl_add_u64 v[232:233], s[64:65], 0, v[132:133]
	s_add_i32 m0, s84, 0xc000
	ds_read_b128 v[196:199], v195
	ds_read_b128 v[200:203], v195 offset:1024
	ds_read_b128 v[204:207], v195 offset:2048
	ds_read_b128 v[208:211], v195 offset:3072
	ds_read_b128 v[212:215], v195 offset:4096
	ds_read_b128 v[216:219], v195 offset:5120
	ds_read_b128 v[220:223], v195 offset:6144
	ds_read_b128 v[224:227], v195 offset:7168
	global_load_lds_dwordx4 v[232:233], off
	v_lshl_add_u64 v[232:233], s[64:65], 0, v[134:135]
	s_add_i32 m0, s84, 0xe000
	s_nop 0
	global_load_lds_dwordx4 v[232:233], off
	s_waitcnt lgkmcnt(8)
	s_barrier
	s_waitcnt lgkmcnt(0)
	s_setprio 1
	s_waitcnt lgkmcnt(0)
	v_mfma_f32_16x16x32_bf16 v[128:131], v[148:151], v[196:199], v[128:131]
	v_mfma_f32_16x16x32_bf16 v[124:127], v[156:159], v[196:199], v[124:127]
	v_mfma_f32_16x16x32_bf16 v[108:111], v[148:151], v[204:207], v[108:111]
	v_mfma_f32_16x16x32_bf16 v[100:103], v[156:159], v[204:207], v[100:103]
	v_mfma_f32_16x16x32_bf16 v[88:91], v[148:151], v[212:215], v[88:91]
	v_mfma_f32_16x16x32_bf16 v[84:87], v[156:159], v[212:215], v[84:87]
	v_mfma_f32_16x16x32_bf16 v[56:59], v[148:151], v[220:223], v[56:59]
	v_mfma_f32_16x16x32_bf16 v[44:47], v[156:159], v[220:223], v[44:47]
	v_mfma_f32_16x16x32_bf16 v[128:131], v[152:155], v[200:203], v[128:131]
	v_mfma_f32_16x16x32_bf16 v[124:127], v[160:163], v[200:203], v[124:127]
	v_mfma_f32_16x16x32_bf16 v[108:111], v[152:155], v[208:211], v[108:111]
	v_mfma_f32_16x16x32_bf16 v[100:103], v[160:163], v[208:211], v[100:103]
	v_mfma_f32_16x16x32_bf16 v[88:91], v[152:155], v[216:219], v[88:91]
	v_mfma_f32_16x16x32_bf16 v[84:87], v[160:163], v[216:219], v[84:87]
	v_mfma_f32_16x16x32_bf16 v[56:59], v[152:155], v[224:227], v[56:59]
	v_mfma_f32_16x16x32_bf16 v[44:47], v[160:163], v[224:227], v[44:47]
	s_setprio 0
	s_barrier
	s_add_i32 s7, 0, 0x14000
	s_add_i32 s33, s33, s87
	v_lshl_add_u64 v[248:249], s[8:9], 0, v[138:139]
	s_add_u32 s8, s8, s34
	v_add_u32_e32 v244, s7, v165
	s_mov_b32 m0, s33
	s_addc_u32 s9, s9, s35
	ds_read_b128 v[232:235], v244
	ds_read_b128 v[236:239], v244 offset:1024
	ds_read_b128 v[240:243], v244 offset:2048
	ds_read_b128 v[244:247], v244 offset:3072
	global_load_lds_dwordx4 v[248:249], off
	v_lshl_add_u64 v[250:251], s[8:9], 0, v[138:139]
	s_add_i32 m0, s33, 0x2000
	s_nop 0
	global_load_lds_dwordx4 v[250:251], off
	s_waitcnt vmcnt(10)
	s_barrier
	s_waitcnt lgkmcnt(0)
	s_setprio 1
	s_waitcnt lgkmcnt(0)
	v_mfma_f32_16x16x32_bf16 v[120:123], v[232:235], v[196:199], v[120:123]
	v_mfma_f32_16x16x32_bf16 v[116:119], v[240:243], v[196:199], v[116:119]
	v_mfma_f32_16x16x32_bf16 v[112:115], v[232:235], v[204:207], v[112:115]
	v_mfma_f32_16x16x32_bf16 v[104:107], v[240:243], v[204:207], v[104:107]
	v_mfma_f32_16x16x32_bf16 v[96:99], v[232:235], v[212:215], v[96:99]
	v_mfma_f32_16x16x32_bf16 v[92:95], v[240:243], v[212:215], v[92:95]
	v_mfma_f32_16x16x32_bf16 v[80:83], v[232:235], v[220:223], v[80:83]
	v_mfma_f32_16x16x32_bf16 v[76:79], v[240:243], v[220:223], v[76:79]
	v_mfma_f32_16x16x32_bf16 v[120:123], v[236:239], v[200:203], v[120:123]
	v_mfma_f32_16x16x32_bf16 v[116:119], v[244:247], v[200:203], v[116:119]
	v_mfma_f32_16x16x32_bf16 v[112:115], v[236:239], v[208:211], v[112:115]
	v_mfma_f32_16x16x32_bf16 v[104:107], v[244:247], v[208:211], v[104:107]
	v_mfma_f32_16x16x32_bf16 v[96:99], v[236:239], v[216:219], v[96:99]
	v_mfma_f32_16x16x32_bf16 v[92:95], v[244:247], v[216:219], v[92:95]
	v_mfma_f32_16x16x32_bf16 v[80:83], v[236:239], v[224:227], v[80:83]
	v_mfma_f32_16x16x32_bf16 v[76:79], v[244:247], v[224:227], v[76:79]
	s_setprio 0
	s_add_u32 s76, s2, s30
	s_mov_b32 m0, s84
	v_lshl_add_u64 v[250:251], s[2:3], 0, v[140:141]
	s_addc_u32 s77, s3, s31
	s_barrier
	ds_read_b128 v[196:199], v195 offset:16384
	ds_read_b128 v[200:203], v195 offset:17408
	ds_read_b128 v[204:207], v195 offset:18432
	ds_read_b128 v[208:211], v195 offset:19456
	ds_read_b128 v[212:215], v195 offset:20480
	ds_read_b128 v[216:219], v195 offset:21504
	ds_read_b128 v[220:223], v195 offset:22528
	ds_read_b128 v[224:227], v195 offset:23552
	global_load_lds_dwordx4 v[250:251], off
	v_lshl_add_u64 v[252:253], s[76:77], 0, v[140:141]
	s_mov_b32 m0, s93
	s_nop 0
	global_load_lds_dwordx4 v[252:253], off
	s_barrier
	s_waitcnt lgkmcnt(0)
	s_setprio 1
	s_waitcnt lgkmcnt(0)
	v_mfma_f32_16x16x32_bf16 v[64:67], v[148:151], v[196:199], v[64:67]
	v_mfma_f32_16x16x32_bf16 v[60:63], v[156:159], v[196:199], v[60:63]
	v_mfma_f32_16x16x32_bf16 v[40:43], v[148:151], v[204:207], v[40:43]
	v_mfma_f32_16x16x32_bf16 v[36:39], v[156:159], v[204:207], v[36:39]
	v_mfma_f32_16x16x32_bf16 v[22:25], v[148:151], v[212:215], v[22:25]
	v_mfma_f32_16x16x32_bf16 v[18:21], v[156:159], v[212:215], v[18:21]
	v_mfma_f32_16x16x32_bf16 v[6:9], v[148:151], v[220:223], v[6:9]
	v_mfma_f32_16x16x32_bf16 v[2:5], v[156:159], v[220:223], v[2:5]
	v_mfma_f32_16x16x32_bf16 v[64:67], v[152:155], v[200:203], v[64:67]
	v_mfma_f32_16x16x32_bf16 v[60:63], v[160:163], v[200:203], v[60:63]
	v_mfma_f32_16x16x32_bf16 v[40:43], v[152:155], v[208:211], v[40:43]
	v_mfma_f32_16x16x32_bf16 v[36:39], v[160:163], v[208:211], v[36:39]
	v_mfma_f32_16x16x32_bf16 v[22:25], v[152:155], v[216:219], v[22:25]
	v_mfma_f32_16x16x32_bf16 v[18:21], v[160:163], v[216:219], v[18:21]
	v_mfma_f32_16x16x32_bf16 v[6:9], v[152:155], v[224:227], v[6:9]
	v_mfma_f32_16x16x32_bf16 v[2:5], v[160:163], v[224:227], v[2:5]
	s_setprio 0
	s_barrier
	s_add_u32 s2, s8, s34
	s_addc_u32 s3, s9, s35
	s_add_i32 s7, s7, s87
	s_add_u32 s8, s2, s34
	v_lshl_add_u64 v[148:149], s[2:3], 0, v[138:139]
	s_mov_b32 m0, s7
	s_addc_u32 s9, s3, s35
	global_load_lds_dwordx4 v[148:149], off
	v_lshl_add_u64 v[252:253], s[8:9], 0, v[138:139]
	s_add_i32 m0, s7, 0x2000
	s_nop 0
	global_load_lds_dwordx4 v[252:253], off
	s_waitcnt vmcnt(8)
	s_barrier
	s_setprio 1
	v_mfma_f32_16x16x32_bf16 v[72:75], v[232:235], v[196:199], v[72:75]
	v_mfma_f32_16x16x32_bf16 v[68:71], v[240:243], v[196:199], v[68:71]
	v_mfma_f32_16x16x32_bf16 v[52:55], v[232:235], v[204:207], v[52:55]
	v_mfma_f32_16x16x32_bf16 v[48:51], v[240:243], v[204:207], v[48:51]
	v_mfma_f32_16x16x32_bf16 v[32:35], v[232:235], v[212:215], v[32:35]
	v_mfma_f32_16x16x32_bf16 v[28:31], v[240:243], v[212:215], v[28:31]
	v_mfma_f32_16x16x32_bf16 v[14:17], v[232:235], v[220:223], v[14:17]
	v_mfma_f32_16x16x32_bf16 v[10:13], v[240:243], v[220:223], v[10:13]
	v_mfma_f32_16x16x32_bf16 v[72:75], v[236:239], v[200:203], v[72:75]
	v_mfma_f32_16x16x32_bf16 v[68:71], v[244:247], v[200:203], v[68:71]
	v_mfma_f32_16x16x32_bf16 v[52:55], v[236:239], v[208:211], v[52:55]
	v_mfma_f32_16x16x32_bf16 v[48:51], v[244:247], v[208:211], v[48:51]
	v_mfma_f32_16x16x32_bf16 v[32:35], v[236:239], v[216:219], v[32:35]
	v_mfma_f32_16x16x32_bf16 v[28:31], v[244:247], v[216:219], v[28:31]
	v_mfma_f32_16x16x32_bf16 v[14:17], v[236:239], v[224:227], v[14:17]
	v_mfma_f32_16x16x32_bf16 v[10:13], v[244:247], v[224:227], v[10:13]
	s_setprio 0
	s_add_i32 s7, 0, 0x18000
	v_add_u32_e32 v160, s7, v165
	s_barrier
	ds_read_b128 v[148:151], v160
	ds_read_b128 v[152:155], v160 offset:1024
	ds_read_b128 v[156:159], v160 offset:2048
	ds_read_b128 v[160:163], v160 offset:3072
	s_add_u32 s8, s76, s30
	s_addc_u32 s9, s77, s31
	s_add_u32 s76, s8, s30
	s_mov_b32 m0, s28
	v_lshl_add_u64 v[232:233], s[8:9], 0, v[140:141]
	s_addc_u32 s77, s9, s31
	ds_read_b128 v[196:199], v195 offset:32768
	ds_read_b128 v[200:203], v195 offset:33792
	ds_read_b128 v[204:207], v195 offset:34816
	ds_read_b128 v[208:211], v195 offset:35840
	ds_read_b128 v[212:215], v195 offset:36864
	ds_read_b128 v[216:219], v195 offset:37888
	ds_read_b128 v[220:223], v195 offset:38912
	ds_read_b128 v[224:227], v195 offset:39936
	global_load_lds_dwordx4 v[232:233], off
	v_lshl_add_u64 v[232:233], s[76:77], 0, v[140:141]
	s_mov_b32 m0, s29
	s_nop 0
	global_load_lds_dwordx4 v[232:233], off
	s_waitcnt lgkmcnt(8)
	s_barrier
	s_waitcnt lgkmcnt(0)
	s_setprio 1
	s_waitcnt lgkmcnt(0)
	v_mfma_f32_16x16x32_bf16 v[128:131], v[148:151], v[196:199], v[128:131]
	v_mfma_f32_16x16x32_bf16 v[124:127], v[156:159], v[196:199], v[124:127]
	v_mfma_f32_16x16x32_bf16 v[108:111], v[148:151], v[204:207], v[108:111]
	v_mfma_f32_16x16x32_bf16 v[100:103], v[156:159], v[204:207], v[100:103]
	v_mfma_f32_16x16x32_bf16 v[88:91], v[148:151], v[212:215], v[88:91]
	v_mfma_f32_16x16x32_bf16 v[84:87], v[156:159], v[212:215], v[84:87]
	v_mfma_f32_16x16x32_bf16 v[56:59], v[148:151], v[220:223], v[56:59]
	v_mfma_f32_16x16x32_bf16 v[44:47], v[156:159], v[220:223], v[44:47]
	v_mfma_f32_16x16x32_bf16 v[128:131], v[152:155], v[200:203], v[128:131]
	v_mfma_f32_16x16x32_bf16 v[124:127], v[160:163], v[200:203], v[124:127]
	v_mfma_f32_16x16x32_bf16 v[108:111], v[152:155], v[208:211], v[108:111]
	v_mfma_f32_16x16x32_bf16 v[100:103], v[160:163], v[208:211], v[100:103]
	v_mfma_f32_16x16x32_bf16 v[88:91], v[152:155], v[216:219], v[88:91]
	v_mfma_f32_16x16x32_bf16 v[84:87], v[160:163], v[216:219], v[84:87]
	v_mfma_f32_16x16x32_bf16 v[56:59], v[152:155], v[224:227], v[56:59]
	v_mfma_f32_16x16x32_bf16 v[44:47], v[160:163], v[224:227], v[44:47]
	s_setprio 0
	s_barrier
	s_add_i32 s33, 0, 0x1c000
	s_add_i32 s7, s7, s87
	s_add_u32 s2, s2, s94
	v_add_u32_e32 v244, s33, v165
	v_lshl_add_u64 v[248:249], v[248:249], 0, s[16:17]
	s_mov_b32 m0, s7
	s_addc_u32 s3, s3, s95
	ds_read_b128 v[232:235], v244
	ds_read_b128 v[236:239], v244 offset:1024
	ds_read_b128 v[240:243], v244 offset:2048
	ds_read_b128 v[244:247], v244 offset:3072
	global_load_lds_dwordx4 v[248:249], off
	v_lshl_add_u64 v[248:249], s[2:3], 0, v[138:139]
	v_lshl_add_u64 v[248:249], v[248:249], 0, s[16:17]
	s_add_i32 m0, s7, 0x2000
	s_nop 0
	global_load_lds_dwordx4 v[248:249], off
	s_waitcnt vmcnt(10)
	s_barrier
	s_waitcnt lgkmcnt(0)
	s_setprio 1
	s_waitcnt lgkmcnt(0)
	v_mfma_f32_16x16x32_bf16 v[120:123], v[232:235], v[196:199], v[120:123]
	v_mfma_f32_16x16x32_bf16 v[116:119], v[240:243], v[196:199], v[116:119]
	v_mfma_f32_16x16x32_bf16 v[112:115], v[232:235], v[204:207], v[112:115]
	v_mfma_f32_16x16x32_bf16 v[104:107], v[240:243], v[204:207], v[104:107]
	v_mfma_f32_16x16x32_bf16 v[96:99], v[232:235], v[212:215], v[96:99]
	v_mfma_f32_16x16x32_bf16 v[92:95], v[240:243], v[212:215], v[92:95]
	v_mfma_f32_16x16x32_bf16 v[80:83], v[232:235], v[220:223], v[80:83]
	v_mfma_f32_16x16x32_bf16 v[76:79], v[240:243], v[220:223], v[76:79]
	v_mfma_f32_16x16x32_bf16 v[120:123], v[236:239], v[200:203], v[120:123]
	v_mfma_f32_16x16x32_bf16 v[116:119], v[244:247], v[200:203], v[116:119]
	v_mfma_f32_16x16x32_bf16 v[112:115], v[236:239], v[208:211], v[112:115]
	v_mfma_f32_16x16x32_bf16 v[104:107], v[244:247], v[208:211], v[104:107]
	v_mfma_f32_16x16x32_bf16 v[96:99], v[236:239], v[216:219], v[96:99]
	v_mfma_f32_16x16x32_bf16 v[92:95], v[244:247], v[216:219], v[92:95]
	v_mfma_f32_16x16x32_bf16 v[80:83], v[236:239], v[224:227], v[80:83]
	v_mfma_f32_16x16x32_bf16 v[76:79], v[244:247], v[224:227], v[76:79]
	s_setprio 0
	s_add_u32 s8, s8, s96
	s_mov_b32 m0, s40
	v_lshl_add_u64 v[248:249], v[250:251], 0, s[16:17]
	s_addc_u32 s9, s9, s97
	s_barrier
	ds_read_b128 v[196:199], v195 offset:49152
	ds_read_b128 v[200:203], v195 offset:50176
	ds_read_b128 v[204:207], v195 offset:51200
	ds_read_b128 v[208:211], v195 offset:52224
	ds_read_b128 v[212:215], v195 offset:53248
	ds_read_b128 v[216:219], v195 offset:54272
	ds_read_b128 v[220:223], v195 offset:55296
	ds_read_b128 v[224:227], v195 offset:56320
	global_load_lds_dwordx4 v[248:249], off
	v_lshl_add_u64 v[248:249], s[8:9], 0, v[140:141]
	v_lshl_add_u64 v[248:249], v[248:249], 0, s[16:17]
	s_mov_b32 m0, s41
	s_nop 0
	global_load_lds_dwordx4 v[248:249], off
	s_barrier
	s_waitcnt lgkmcnt(0)
	s_setprio 1
	s_waitcnt lgkmcnt(0)
	v_mfma_f32_16x16x32_bf16 v[64:67], v[148:151], v[196:199], v[64:67]
	v_mfma_f32_16x16x32_bf16 v[60:63], v[156:159], v[196:199], v[60:63]
	v_mfma_f32_16x16x32_bf16 v[40:43], v[148:151], v[204:207], v[40:43]
	v_mfma_f32_16x16x32_bf16 v[36:39], v[156:159], v[204:207], v[36:39]
	v_mfma_f32_16x16x32_bf16 v[22:25], v[148:151], v[212:215], v[22:25]
	v_mfma_f32_16x16x32_bf16 v[18:21], v[156:159], v[212:215], v[18:21]
	v_mfma_f32_16x16x32_bf16 v[6:9], v[148:151], v[220:223], v[6:9]
	v_mfma_f32_16x16x32_bf16 v[2:5], v[156:159], v[220:223], v[2:5]
	v_mfma_f32_16x16x32_bf16 v[64:67], v[152:155], v[200:203], v[64:67]
	v_mfma_f32_16x16x32_bf16 v[60:63], v[160:163], v[200:203], v[60:63]
	v_mfma_f32_16x16x32_bf16 v[40:43], v[152:155], v[208:211], v[40:43]
	v_mfma_f32_16x16x32_bf16 v[36:39], v[160:163], v[208:211], v[36:39]
	v_mfma_f32_16x16x32_bf16 v[22:25], v[152:155], v[216:219], v[22:25]
	v_mfma_f32_16x16x32_bf16 v[18:21], v[160:163], v[216:219], v[18:21]
	v_mfma_f32_16x16x32_bf16 v[6:9], v[152:155], v[224:227], v[6:9]
	v_mfma_f32_16x16x32_bf16 v[2:5], v[160:163], v[224:227], v[2:5]
	s_setprio 0
	s_barrier
	s_add_u32 s2, s2, s34
	s_addc_u32 s3, s3, s35
	v_lshl_add_u64 v[148:149], s[2:3], 0, v[138:139]
	s_add_i32 s2, s33, s87
	v_lshl_add_u64 v[148:149], v[148:149], 0, s[16:17]
	s_mov_b32 m0, s2
	s_nop 0
	global_load_lds_dwordx4 v[148:149], off
	v_lshl_add_u64 v[148:149], v[252:253], 0, s[16:17]
	s_add_i32 m0, s2, 0x2000
	s_nop 0
	global_load_lds_dwordx4 v[148:149], off
	s_waitcnt vmcnt(8)
	s_barrier
	s_setprio 1
	v_mfma_f32_16x16x32_bf16 v[72:75], v[232:235], v[196:199], v[72:75]
	v_mfma_f32_16x16x32_bf16 v[68:71], v[240:243], v[196:199], v[68:71]
	v_mfma_f32_16x16x32_bf16 v[52:55], v[232:235], v[204:207], v[52:55]
	v_mfma_f32_16x16x32_bf16 v[48:51], v[240:243], v[204:207], v[48:51]
	v_mfma_f32_16x16x32_bf16 v[32:35], v[232:235], v[212:215], v[32:35]
	v_mfma_f32_16x16x32_bf16 v[28:31], v[240:243], v[212:215], v[28:31]
	v_mfma_f32_16x16x32_bf16 v[14:17], v[232:235], v[220:223], v[14:17]
	v_mfma_f32_16x16x32_bf16 v[10:13], v[240:243], v[220:223], v[10:13]
	v_mfma_f32_16x16x32_bf16 v[72:75], v[236:239], v[200:203], v[72:75]
	v_mfma_f32_16x16x32_bf16 v[68:71], v[244:247], v[200:203], v[68:71]
	v_mfma_f32_16x16x32_bf16 v[52:55], v[236:239], v[208:211], v[52:55]
	v_mfma_f32_16x16x32_bf16 v[48:51], v[244:247], v[208:211], v[48:51]
	v_mfma_f32_16x16x32_bf16 v[32:35], v[236:239], v[216:219], v[32:35]
	v_mfma_f32_16x16x32_bf16 v[28:31], v[244:247], v[216:219], v[28:31]
	v_mfma_f32_16x16x32_bf16 v[14:17], v[236:239], v[224:227], v[14:17]
	v_mfma_f32_16x16x32_bf16 v[10:13], v[244:247], v[224:227], v[10:13]
	s_setprio 0
	s_add_u32 s0, s0, 0x100
	s_addc_u32 s1, s1, 0
	v_lshl_add_u64 v[134:135], v[134:135], 0, s[20:21]
	v_lshl_add_u64 v[132:133], v[132:133], 0, s[20:21]
	s_cmp_ge_u32 s6, s86
	s_mov_b32 s2, s6
	s_barrier
	s_cbranch_scc0 .LBB0_894
	s_and_b64 vcc, exec, s[26:27]
	s_cbranch_vccz .LBB0_1126
	v_add_u32_e32 v148, s81, v166
	v_add_u32_e32 v132, s62, v168
	s_mov_b64 s[2:3], -1
	s_mov_b64 s[0:1], 0
	s_cmp_lt_i32 s63, 4
	s_mov_b64 s[76:77], 0
	s_cbranch_scc1 .LBB0_928
	s_cmp_gt_i32 s63, 6
	s_cbranch_scc0 .LBB0_921
	s_cmp_gt_i32 s63, 7
	s_cbranch_scc0 .LBB0_902
	s_cmp_eq_u32 s63, 8
	s_mov_b64 s[76:77], -1
	s_cbranch_scc0 .LBB0_901
	v_ashrrev_i32_e32 v149, 31, v148
	v_lshl_add_u64 v[134:135], v[148:149], 2, s[42:43]
	global_load_dword v198, v[134:135], off
	global_load_dword v200, v[134:135], off offset:64
	global_load_dword v202, v[134:135], off offset:128
	global_load_dword v204, v[134:135], off offset:192
	global_load_dword v206, v[134:135], off offset:512
	global_load_dword v208, v[134:135], off offset:576
	global_load_dword v210, v[134:135], off offset:640
	global_load_dword v212, v[134:135], off offset:704
	s_mov_b32 s6, 0x800000
	v_add_u32_e32 v152, v132, v167
	v_mov_b64_e32 v[150:151], s[44:45]
	s_movk_i32 s7, 0x2c00
	v_ashrrev_i32_e32 v153, 31, v152
	v_mad_i64_i32 v[160:161], s[2:3], v148, s7, v[150:151]
	v_lshlrev_b64 v[152:153], 1, v[152:153]
	v_lshl_add_u64 v[160:161], v[160:161], 0, v[152:153]
	s_mov_b64 s[2:3], 0x2c000
	v_lshl_add_u64 v[214:215], v[160:161], 0, s[2:3]
	v_lshl_add_u64 v[216:217], v[214:215], 0, s[2:3]
	v_lshl_add_u64 v[218:219], v[216:217], 0, s[2:3]
	s_mov_b64 s[2:3], 0x160000
	v_lshl_add_u64 v[220:221], v[160:161], 0, s[2:3]
	v_lshl_add_u64 v[222:223], v[214:215], 0, s[2:3]
	v_lshl_add_u64 v[224:225], v[216:217], 0, s[2:3]
	v_lshl_add_u64 v[226:227], v[218:219], 0, s[2:3]
	s_mov_b64 s[76:77], 0
	s_waitcnt vmcnt(0)
	v_fmamk_f32 v198, v198, 0x3a800000, v172
	v_fmamk_f32 v200, v200, 0x3a800000, v172
	v_fmamk_f32 v202, v202, 0x3a800000, v172
	v_fmamk_f32 v204, v204, 0x3a800000, v172
	v_fmamk_f32 v206, v206, 0x3a800000, v172
	v_fmamk_f32 v208, v208, 0x3a800000, v172
	v_fmamk_f32 v210, v210, 0x3a800000, v172
	v_fmamk_f32 v212, v212, 0x3a800000, v172
	v_rsq_f32_e32 v198, v198
	v_rsq_f32_e32 v200, v200
	v_rsq_f32_e32 v202, v202
	v_rsq_f32_e32 v204, v204
	v_rsq_f32_e32 v206, v206
	v_rsq_f32_e32 v208, v208
	v_rsq_f32_e32 v210, v210
	v_rsq_f32_e32 v212, v212
	s_nop 0
	v_pk_mul_f32 v[128:129], v[128:129], v[198:199] op_sel_hi:[1,0]
	v_pk_mul_f32 v[130:131], v[130:131], v[198:199] op_sel_hi:[1,0]
	v_pk_mul_f32 v[124:125], v[124:125], v[198:199] op_sel_hi:[1,0]
	v_pk_mul_f32 v[126:127], v[126:127], v[198:199] op_sel_hi:[1,0]
	v_cvt_pk_bf16_f32 v128, v128, v129
	v_cvt_pk_bf16_f32 v129, v130, v131
	v_cvt_pk_bf16_f32 v130, v124, v125
	v_cvt_pk_bf16_f32 v131, v126, v127
	global_store_dwordx4 v[160:161], v[128:131], off
	v_pk_mul_f32 v[120:121], v[120:121], v[198:199] op_sel_hi:[1,0]
	v_pk_mul_f32 v[122:123], v[122:123], v[198:199] op_sel_hi:[1,0]
	v_pk_mul_f32 v[116:117], v[116:117], v[198:199] op_sel_hi:[1,0]
	v_pk_mul_f32 v[118:119], v[118:119], v[198:199] op_sel_hi:[1,0]
	v_cvt_pk_bf16_f32 v120, v120, v121
	v_cvt_pk_bf16_f32 v121, v122, v123
	v_cvt_pk_bf16_f32 v122, v116, v117
	v_cvt_pk_bf16_f32 v123, v118, v119
	global_store_dwordx4 v[160:161], v[120:123], off offset:256
	v_pk_mul_f32 v[108:109], v[108:109], v[200:201] op_sel_hi:[1,0]
	v_pk_mul_f32 v[110:111], v[110:111], v[200:201] op_sel_hi:[1,0]
	v_pk_mul_f32 v[100:101], v[100:101], v[200:201] op_sel_hi:[1,0]
	v_pk_mul_f32 v[102:103], v[102:103], v[200:201] op_sel_hi:[1,0]
	v_cvt_pk_bf16_f32 v108, v108, v109
	v_cvt_pk_bf16_f32 v109, v110, v111
	v_cvt_pk_bf16_f32 v110, v100, v101
	v_cvt_pk_bf16_f32 v111, v102, v103
	global_store_dwordx4 v[214:215], v[108:111], off
	v_pk_mul_f32 v[112:113], v[112:113], v[200:201] op_sel_hi:[1,0]
	v_pk_mul_f32 v[114:115], v[114:115], v[200:201] op_sel_hi:[1,0]
	v_pk_mul_f32 v[104:105], v[104:105], v[200:201] op_sel_hi:[1,0]
	v_pk_mul_f32 v[106:107], v[106:107], v[200:201] op_sel_hi:[1,0]
	v_cvt_pk_bf16_f32 v112, v112, v113
	v_cvt_pk_bf16_f32 v113, v114, v115
	v_cvt_pk_bf16_f32 v114, v104, v105
	v_cvt_pk_bf16_f32 v115, v106, v107
	global_store_dwordx4 v[214:215], v[112:115], off offset:256
	v_pk_mul_f32 v[88:89], v[88:89], v[202:203] op_sel_hi:[1,0]
	v_pk_mul_f32 v[90:91], v[90:91], v[202:203] op_sel_hi:[1,0]
	v_pk_mul_f32 v[84:85], v[84:85], v[202:203] op_sel_hi:[1,0]
	v_pk_mul_f32 v[86:87], v[86:87], v[202:203] op_sel_hi:[1,0]
	v_cvt_pk_bf16_f32 v88, v88, v89
	v_cvt_pk_bf16_f32 v89, v90, v91
	v_cvt_pk_bf16_f32 v90, v84, v85
	v_cvt_pk_bf16_f32 v91, v86, v87
	global_store_dwordx4 v[216:217], v[88:91], off
	v_pk_mul_f32 v[96:97], v[96:97], v[202:203] op_sel_hi:[1,0]
	v_pk_mul_f32 v[98:99], v[98:99], v[202:203] op_sel_hi:[1,0]
	v_pk_mul_f32 v[92:93], v[92:93], v[202:203] op_sel_hi:[1,0]
	v_pk_mul_f32 v[94:95], v[94:95], v[202:203] op_sel_hi:[1,0]
	v_cvt_pk_bf16_f32 v96, v96, v97
	v_cvt_pk_bf16_f32 v97, v98, v99
	v_cvt_pk_bf16_f32 v98, v92, v93
	v_cvt_pk_bf16_f32 v99, v94, v95
	global_store_dwordx4 v[216:217], v[96:99], off offset:256
	v_pk_mul_f32 v[56:57], v[56:57], v[204:205] op_sel_hi:[1,0]
	v_pk_mul_f32 v[58:59], v[58:59], v[204:205] op_sel_hi:[1,0]
	v_pk_mul_f32 v[44:45], v[44:45], v[204:205] op_sel_hi:[1,0]
	v_pk_mul_f32 v[46:47], v[46:47], v[204:205] op_sel_hi:[1,0]
	v_cvt_pk_bf16_f32 v56, v56, v57
	v_cvt_pk_bf16_f32 v57, v58, v59
	v_cvt_pk_bf16_f32 v58, v44, v45
	v_cvt_pk_bf16_f32 v59, v46, v47
	global_store_dwordx4 v[218:219], v[56:59], off
	v_pk_mul_f32 v[80:81], v[80:81], v[204:205] op_sel_hi:[1,0]
	v_pk_mul_f32 v[82:83], v[82:83], v[204:205] op_sel_hi:[1,0]
	v_pk_mul_f32 v[76:77], v[76:77], v[204:205] op_sel_hi:[1,0]
	v_pk_mul_f32 v[78:79], v[78:79], v[204:205] op_sel_hi:[1,0]
	v_cvt_pk_bf16_f32 v80, v80, v81
	v_cvt_pk_bf16_f32 v81, v82, v83
	v_cvt_pk_bf16_f32 v82, v76, v77
	v_cvt_pk_bf16_f32 v83, v78, v79
	global_store_dwordx4 v[218:219], v[80:83], off offset:256
	v_pk_mul_f32 v[64:65], v[64:65], v[206:207] op_sel_hi:[1,0]
	v_pk_mul_f32 v[66:67], v[66:67], v[206:207] op_sel_hi:[1,0]
	v_pk_mul_f32 v[60:61], v[60:61], v[206:207] op_sel_hi:[1,0]
	v_pk_mul_f32 v[62:63], v[62:63], v[206:207] op_sel_hi:[1,0]
	v_cvt_pk_bf16_f32 v64, v64, v65
	v_cvt_pk_bf16_f32 v65, v66, v67
	v_cvt_pk_bf16_f32 v66, v60, v61
	v_cvt_pk_bf16_f32 v67, v62, v63
	global_store_dwordx4 v[220:221], v[64:67], off
	v_pk_mul_f32 v[72:73], v[72:73], v[206:207] op_sel_hi:[1,0]
	v_pk_mul_f32 v[74:75], v[74:75], v[206:207] op_sel_hi:[1,0]
	v_pk_mul_f32 v[68:69], v[68:69], v[206:207] op_sel_hi:[1,0]
	v_pk_mul_f32 v[70:71], v[70:71], v[206:207] op_sel_hi:[1,0]
	v_cvt_pk_bf16_f32 v72, v72, v73
	v_cvt_pk_bf16_f32 v73, v74, v75
	v_cvt_pk_bf16_f32 v74, v68, v69
	v_cvt_pk_bf16_f32 v75, v70, v71
	global_store_dwordx4 v[220:221], v[72:75], off offset:256
	v_pk_mul_f32 v[40:41], v[40:41], v[208:209] op_sel_hi:[1,0]
	v_pk_mul_f32 v[42:43], v[42:43], v[208:209] op_sel_hi:[1,0]
	v_pk_mul_f32 v[36:37], v[36:37], v[208:209] op_sel_hi:[1,0]
	v_pk_mul_f32 v[38:39], v[38:39], v[208:209] op_sel_hi:[1,0]
	v_cvt_pk_bf16_f32 v40, v40, v41
	v_cvt_pk_bf16_f32 v41, v42, v43
	v_cvt_pk_bf16_f32 v42, v36, v37
	v_cvt_pk_bf16_f32 v43, v38, v39
	global_store_dwordx4 v[222:223], v[40:43], off
	v_pk_mul_f32 v[52:53], v[52:53], v[208:209] op_sel_hi:[1,0]
	v_pk_mul_f32 v[54:55], v[54:55], v[208:209] op_sel_hi:[1,0]
	v_pk_mul_f32 v[48:49], v[48:49], v[208:209] op_sel_hi:[1,0]
	v_pk_mul_f32 v[50:51], v[50:51], v[208:209] op_sel_hi:[1,0]
	v_cvt_pk_bf16_f32 v52, v52, v53
	v_cvt_pk_bf16_f32 v53, v54, v55
	v_cvt_pk_bf16_f32 v54, v48, v49
	v_cvt_pk_bf16_f32 v55, v50, v51
	global_store_dwordx4 v[222:223], v[52:55], off offset:256
	v_pk_mul_f32 v[22:23], v[22:23], v[210:211] op_sel_hi:[1,0]
	v_pk_mul_f32 v[24:25], v[24:25], v[210:211] op_sel_hi:[1,0]
	v_pk_mul_f32 v[18:19], v[18:19], v[210:211] op_sel_hi:[1,0]
	v_pk_mul_f32 v[20:21], v[20:21], v[210:211] op_sel_hi:[1,0]
	v_cvt_pk_bf16_f32 v22, v22, v23
	v_cvt_pk_bf16_f32 v23, v24, v25
	v_cvt_pk_bf16_f32 v24, v18, v19
	v_cvt_pk_bf16_f32 v25, v20, v21
	global_store_dwordx4 v[224:225], v[22:25], off
	v_pk_mul_f32 v[32:33], v[32:33], v[210:211] op_sel_hi:[1,0]
	v_pk_mul_f32 v[34:35], v[34:35], v[210:211] op_sel_hi:[1,0]
	v_pk_mul_f32 v[28:29], v[28:29], v[210:211] op_sel_hi:[1,0]
	v_pk_mul_f32 v[30:31], v[30:31], v[210:211] op_sel_hi:[1,0]
	v_cvt_pk_bf16_f32 v32, v32, v33
	v_cvt_pk_bf16_f32 v33, v34, v35
	v_cvt_pk_bf16_f32 v34, v28, v29
	v_cvt_pk_bf16_f32 v35, v30, v31
	global_store_dwordx4 v[224:225], v[32:35], off offset:256
	v_pk_mul_f32 v[6:7], v[6:7], v[212:213] op_sel_hi:[1,0]
	v_pk_mul_f32 v[8:9], v[8:9], v[212:213] op_sel_hi:[1,0]
	v_pk_mul_f32 v[2:3], v[2:3], v[212:213] op_sel_hi:[1,0]
	v_pk_mul_f32 v[4:5], v[4:5], v[212:213] op_sel_hi:[1,0]
	v_cvt_pk_bf16_f32 v6, v6, v7
	v_cvt_pk_bf16_f32 v7, v8, v9
	v_cvt_pk_bf16_f32 v8, v2, v3
	v_cvt_pk_bf16_f32 v9, v4, v5
	global_store_dwordx4 v[226:227], v[6:9], off
	v_pk_mul_f32 v[14:15], v[14:15], v[212:213] op_sel_hi:[1,0]
	v_pk_mul_f32 v[16:17], v[16:17], v[212:213] op_sel_hi:[1,0]
	v_pk_mul_f32 v[10:11], v[10:11], v[212:213] op_sel_hi:[1,0]
	v_pk_mul_f32 v[12:13], v[12:13], v[212:213] op_sel_hi:[1,0]
	v_cvt_pk_bf16_f32 v14, v14, v15
	v_cvt_pk_bf16_f32 v15, v16, v17
	v_cvt_pk_bf16_f32 v16, v10, v11
	v_cvt_pk_bf16_f32 v17, v12, v13
	global_store_dwordx4 v[226:227], v[14:17], off offset:256
